# P0 w_kv_b weight items: the 8 guarded (gain, weight) load pairs of an iteration issued together with one wait instead of a wait per pair
# baseline (speedup 1.0000x reference)
; DI void p0_weight_item(const Params& p, LAS float* scr, int mid, int t, int lane) {
;     ...
; #pragma unroll 8
;     for (int i = 0; i < 32; ++i) {
;         const int kk = 2 * i + (lane >> 5), k = k0 + kk;
;         float gv = 1.f; bool ok = src >= 0;
;         if (mid == 0) gv = p.g_attn[k];
;         else if (mid == 1) gv = p.g_qa[k];
;         else if (mid == 2) { if (k >= K) ok = false; else gv = p.g_kva[k]; }
;         else if (mid == 3) gv = (k < 512) ? p.g_sbo[k] : p.g_mlao[k - 512];
;         else if (mid == 4) gv = p.g_mlp[k];
;         float val = 0.f;
;         if (ok) val = W[(size_t)k * N + src] * gv * sc;
;         scr[kk * 33 + nn] = val;
.LBB0_43:
	s_add_u32 s2, s2, 0x10000
	s_addc_u32 s3, s3, 0
	s_add_u32 s4, s4, 64
	s_addc_u32 s5, s5, 0
	v_add_u32_e32 v68, 0x840, v68
	s_cmp_lg_u32 s2, 0x40000
	v_add_u32_e32 v5, 16, v5
	s_cbranch_scc0 .LBB0_60
.LBB0_44:
	v_mov_b32_e32 v200, 0
	v_mov_b32_e32 v201, 0
	v_mov_b32_e32 v202, 0
	v_mov_b32_e32 v203, 0
	v_mov_b32_e32 v204, 0
	v_mov_b32_e32 v205, 0
	v_mov_b32_e32 v206, 0
	v_mov_b32_e32 v207, 0
	v_mov_b32_e32 v208, 0
	v_mov_b32_e32 v209, 0
	v_mov_b32_e32 v210, 0
	v_mov_b32_e32 v211, 0
	v_mov_b32_e32 v212, 0
	v_mov_b32_e32 v213, 0
	v_mov_b32_e32 v214, 0
	v_mov_b32_e32 v215, 0
	v_lshl_add_u64 v[42:43], s[4:5], 0, v[26:27]
	v_add_u32_e32 v69, -14, v5
	v_cmp_gt_u32_e32 vcc, s33, v69
	s_and_saveexec_b64 s[6:7], vcc
	v_lshl_add_u64 v[216:217], v[40:41], 0, s[2:3]
	v_lshl_add_u64 v[218:219], s[4:5], 0, v[8:9]
	global_load_dword v208, v[218:219], off
	global_load_dword v200, v[216:217], off
	s_or_b64 exec, exec, s[6:7]
	v_add_u32_e32 v69, -12, v5
	v_cmp_gt_u32_e32 vcc, s33, v69
	s_and_saveexec_b64 s[6:7], vcc
	v_lshl_add_u64 v[220:221], v[38:39], 0, s[2:3]
	global_load_dword v209, v[42:43], off offset:8
	global_load_dword v201, v[220:221], off
	s_or_b64 exec, exec, s[6:7]
	v_add_u32_e32 v69, -10, v5
	v_cmp_gt_u32_e32 vcc, s33, v69
	s_and_saveexec_b64 s[6:7], vcc
	v_lshl_add_u64 v[216:217], v[36:37], 0, s[2:3]
	global_load_dword v210, v[42:43], off offset:16
	global_load_dword v202, v[216:217], off
	s_or_b64 exec, exec, s[6:7]
	v_add_u32_e32 v69, -8, v5
	v_cmp_gt_u32_e32 vcc, s33, v69
	s_and_saveexec_b64 s[6:7], vcc
	v_lshl_add_u64 v[220:221], v[34:35], 0, s[2:3]
	global_load_dword v211, v[42:43], off offset:24
	global_load_dword v203, v[220:221], off
	s_or_b64 exec, exec, s[6:7]
	v_add_u32_e32 v69, -6, v5
	v_cmp_gt_u32_e32 vcc, s33, v69
	s_and_saveexec_b64 s[6:7], vcc
	v_lshl_add_u64 v[216:217], v[32:33], 0, s[2:3]
	global_load_dword v212, v[42:43], off offset:32
	global_load_dword v204, v[216:217], off
	s_or_b64 exec, exec, s[6:7]
	v_add_u32_e32 v69, -4, v5
	v_cmp_gt_u32_e32 vcc, s33, v69
	s_and_saveexec_b64 s[6:7], vcc
	v_lshl_add_u64 v[220:221], v[30:31], 0, s[2:3]
	global_load_dword v213, v[42:43], off offset:40
	global_load_dword v205, v[220:221], off
	s_or_b64 exec, exec, s[6:7]
	v_add_u32_e32 v69, -2, v5
	v_cmp_gt_u32_e32 vcc, s33, v69
	s_and_saveexec_b64 s[6:7], vcc
	v_lshl_add_u64 v[216:217], v[28:29], 0, s[2:3]
	global_load_dword v214, v[42:43], off offset:48
	global_load_dword v206, v[216:217], off
	s_or_b64 exec, exec, s[6:7]
	v_cmp_gt_u32_e32 vcc, s33, v5
	s_and_saveexec_b64 s[6:7], vcc
	v_lshl_add_u64 v[220:221], v[24:25], 0, s[2:3]
	global_load_dword v215, v[42:43], off offset:56
	global_load_dword v207, v[220:221], off
	s_or_b64 exec, exec, s[6:7]
	s_waitcnt vmcnt(0)
	v_mul_f32_e32 v200, v208, v200
	v_mul_f32_e32 v201, v209, v201
	v_mul_f32_e32 v202, v210, v202
	v_mul_f32_e32 v203, v211, v203
	v_mul_f32_e32 v204, v212, v204
	v_mul_f32_e32 v205, v213, v205
	v_mul_f32_e32 v206, v214, v206
	v_mul_f32_e32 v207, v215, v207
	ds_write_b32 v68, v200
	ds_write_b32 v68, v201 offset:264
	ds_write_b32 v68, v202 offset:528
	ds_write_b32 v68, v203 offset:792
	ds_write_b32 v68, v204 offset:1056
	ds_write_b32 v68, v205 offset:1320
	ds_write_b32 v68, v206 offset:1584
	ds_write_b32 v68, v207 offset:1848
	s_branch .LBB0_43
